# layer-1 memory attention: V^T keys staged permuted so each PV operand is one ds_read_b128 (was ds_read2_b64), cross-lane reductions by permlane swaps, staggered SIMD partners
# speedup vs baseline: 1.0097x; 1.0057x over previous
.Lgm_done:
.LBB0_575:
	v_readlane_b32 s4, v244, 35
	v_readlane_b32 s5, v244, 36
	s_andn2_b64 vcc, exec, s[4:5]
	s_cbranch_vccnz .LBB0_582
	v_ashrrev_i32_e32 v118, 1, v83
	v_readlane_b32 s8, v245, 63
	s_add_u32 s4, s6, 0x3e00000
	s_addc_u32 s5, s7, 0
	v_add_u32_e32 v4, s8, v118
	v_ashrrev_i32_e32 v5, 31, v4
	v_readlane_b32 s8, v243, 41
	v_lshlrev_b64 v[4:5], 11, v[4:5]
	v_readlane_b32 s9, v243, 42
	v_lshlrev_b32_e32 v1, 5, v83
	v_lshl_add_u64 v[4:5], s[4:5], 0, v[4:5]
	s_mov_b32 s9, s37
	v_and_b32_e32 v36, 32, v1
	v_lshl_add_u64 v[4:5], v[4:5], 0, s[8:9]
	v_lshlrev_b32_e32 v6, 1, v36
	v_mov_b32_e32 v7, v3
	s_mov_b32 s10, s8
	v_lshl_add_u64 v[32:33], v[4:5], 0, v[6:7]
	s_movk_i32 s8, 0x90
	v_mul_u32_u24_e32 v4, 0x210, v36
	v_and_b32_e32 v5, -2, v83
	v_mul_lo_u32 v1, v118, s8
	v_add3_u32 v121, 0, v4, v5
	v_and_b32_e32 v200, -32, v118
	v_bfe_u32 v201, v118, 2, 2
	v_lshl_or_b32 v200, v201, 3, v200
	v_bfe_u32 v201, v118, 4, 1
	v_lshl_or_b32 v200, v201, 2, v200
	v_and_b32_e32 v201, 3, v118
	v_or_b32_e32 v200, v200, v201
	v_sub_u32_e32 v200, v200, v118
	v_lshl_add_u32 v121, v200, 1, v121
	v_mul_u32_u24_e32 v4, 0x210, v84
	v_add3_u32 v119, 0, v1, v6
	v_add3_u32 v122, 0, v4, v2
	global_load_dwordx4 v[4:7], v[32:33], off offset:1072
	global_load_dwordx4 v[8:11], v[32:33], off offset:1056
	global_load_dwordx4 v[12:15], v[32:33], off offset:1040
	global_load_dwordx4 v[16:19], v[32:33], off offset:1024
	global_load_dwordx4 v[20:23], v[32:33], off offset:1536
	global_load_dwordx4 v[24:27], v[32:33], off offset:1552
	global_load_dwordx4 v[28:31], v[32:33], off offset:1568
	s_nop 0
	global_load_dwordx4 v[32:35], v[32:33], off offset:1584
	v_and_b32_e32 v39, 64, v197
	v_xor_b32_e32 v38, 16, v197
	v_add_u32_e32 v39, 64, v39
	v_cmp_lt_i32_e32 vcc, v38, v39
	v_writelane_b32 v243, s10, 41
	v_mov_b32_e32 v1, v3
	v_cndmask_b32_e32 v38, v197, v38, vcc
	v_lshlrev_b32_e32 v126, 2, v38
	v_xor_b32_e32 v38, 32, v197
	v_cmp_lt_i32_e32 vcc, v38, v39
	v_writelane_b32 v243, s11, 42
	s_movk_i32 s8, 0xffe0
	v_lshl_add_u64 v[0:1], s[6:7], 0, v[0:1]
	s_mov_b64 s[6:7], 0xc200000
	v_mul_u32_u24_e32 v37, 0x90, v84
	v_cndmask_b32_e32 v38, v197, v38, vcc
	v_and_or_b32 v120, v118, s8, v84
	v_lshl_add_u64 v[0:1], v[0:1], 0, s[6:7]
	v_add_u32_e32 v123, 0x2100, v122
	v_add_u32_e32 v124, 0x4200, v122
	v_add_u32_e32 v125, 0x6300, v122
	v_lshlrev_b32_e32 v127, 2, v38
	v_lshlrev_b32_e32 v112, 1, v36
	v_add_u32_e32 v128, v82, v37
	v_readlane_b32 s13, v243, 35
	v_readlane_b32 s10, v243, 31
	s_mov_b32 s11, s2
	s_branch .LBB0_578

.Lma_nostag:
	v_add_u32_e32 v150, 0x9000, v122
	v_add_u32_e32 v151, 0x9000, v123
	v_add_u32_e32 v152, 0x9000, v124
	v_add_u32_e32 v153, 0x9000, v125
	v_bfe_u32 v155, v197, 4, 2
	v_lshlrev_b32_e32 v155, 3, v155
	v_add_u32_e32 v150, v150, v155
	v_add_u32_e32 v151, v151, v155
	v_add_u32_e32 v152, v152, v155
	v_add_u32_e32 v153, v153, v155
	ds_read_b128 v[200:203], v128
	ds_read_b128 v[204:207], v128 offset:64
	ds_read_b128 v[208:211], v128 offset:2304
	ds_read_b128 v[212:215], v128 offset:2368
	ds_read_b128 v[216:219], v128 offset:4608
	ds_read_b128 v[220:223], v128 offset:4672
	ds_read_b128 v[224:227], v128 offset:6912
	ds_read_b128 v[228:231], v128 offset:6976
	s_waitcnt vmcnt(10)
	s_waitcnt lgkmcnt(4)
	v_mfma_f32_16x16x32_bf16 v[44:47], v[200:203], v[108:111], 0
	v_mfma_f32_16x16x32_bf16 v[48:51], v[208:211], v[108:111], 0
	v_mfma_f32_16x16x32_bf16 v[44:47], v[204:207], v[60:63], v[44:47]
	v_mfma_f32_16x16x32_bf16 v[48:51], v[212:215], v[60:63], v[48:51]
	ds_read_b128 v[200:203], v128 offset:9216
	ds_read_b128 v[204:207], v128 offset:9280
	ds_read_b128 v[208:211], v128 offset:11520
	ds_read_b128 v[212:215], v128 offset:11584
	s_waitcnt lgkmcnt(4)
	v_mfma_f32_16x16x32_bf16 v[52:55], v[216:219], v[108:111], 0
	v_mfma_f32_16x16x32_bf16 v[56:59], v[224:227], v[108:111], 0
	v_mfma_f32_16x16x32_bf16 v[52:55], v[220:223], v[60:63], v[52:55]
	v_mfma_f32_16x16x32_bf16 v[56:59], v[228:231], v[60:63], v[56:59]
	ds_read_b128 v[216:219], v128 offset:13824
	ds_read_b128 v[220:223], v128 offset:13888
	ds_read_b128 v[224:227], v128 offset:16128
	ds_read_b128 v[228:231], v128 offset:16192
	s_waitcnt lgkmcnt(4)
	v_mfma_f32_16x16x32_bf16 v[64:67], v[200:203], v[108:111], 0
	v_mfma_f32_16x16x32_bf16 v[68:71], v[208:211], v[108:111], 0
	v_mfma_f32_16x16x32_bf16 v[64:67], v[204:207], v[60:63], v[64:67]
	v_mfma_f32_16x16x32_bf16 v[68:71], v[212:215], v[60:63], v[68:71]
	ds_read_b128 v[200:203], v128 offset:18432
	ds_read_b128 v[204:207], v128 offset:18496
	ds_read_b128 v[208:211], v128 offset:20736
	ds_read_b128 v[212:215], v128 offset:20800
	s_waitcnt lgkmcnt(4)
	v_mfma_f32_16x16x32_bf16 v[72:75], v[216:219], v[108:111], 0
	v_mfma_f32_16x16x32_bf16 v[76:79], v[224:227], v[108:111], 0
	v_mfma_f32_16x16x32_bf16 v[72:75], v[220:223], v[60:63], v[72:75]
	v_mfma_f32_16x16x32_bf16 v[76:79], v[228:231], v[60:63], v[76:79]
	ds_read_b128 v[216:219], v128 offset:23040
	ds_read_b128 v[220:223], v128 offset:23104
	ds_read_b128 v[224:227], v128 offset:25344
	ds_read_b128 v[228:231], v128 offset:25408
	s_waitcnt lgkmcnt(4)
	v_mfma_f32_16x16x32_bf16 v[80:83], v[200:203], v[108:111], 0
	v_mfma_f32_16x16x32_bf16 v[84:87], v[208:211], v[108:111], 0
	v_mfma_f32_16x16x32_bf16 v[80:83], v[204:207], v[60:63], v[80:83]
	v_mfma_f32_16x16x32_bf16 v[84:87], v[212:215], v[60:63], v[84:87]
	ds_read_b128 v[200:203], v128 offset:27648
	ds_read_b128 v[204:207], v128 offset:27712
	ds_read_b128 v[208:211], v128 offset:29952
	ds_read_b128 v[212:215], v128 offset:30016
	s_waitcnt lgkmcnt(4)
	v_mfma_f32_16x16x32_bf16 v[88:91], v[216:219], v[108:111], 0
	v_mfma_f32_16x16x32_bf16 v[92:95], v[224:227], v[108:111], 0
	v_mfma_f32_16x16x32_bf16 v[88:91], v[220:223], v[60:63], v[88:91]
	v_mfma_f32_16x16x32_bf16 v[92:95], v[228:231], v[60:63], v[92:95]
	ds_read_b128 v[216:219], v128 offset:32256
	ds_read_b128 v[220:223], v128 offset:32320
	ds_read_b128 v[224:227], v128 offset:34560
	ds_read_b128 v[228:231], v128 offset:34624
	s_waitcnt lgkmcnt(4)
	v_mfma_f32_16x16x32_bf16 v[96:99], v[200:203], v[108:111], 0
	v_mfma_f32_16x16x32_bf16 v[100:103], v[208:211], v[108:111], 0
	v_mfma_f32_16x16x32_bf16 v[96:99], v[204:207], v[60:63], v[96:99]
	v_mfma_f32_16x16x32_bf16 v[100:103], v[212:215], v[60:63], v[100:103]
	s_waitcnt lgkmcnt(0)
	v_mfma_f32_16x16x32_bf16 v[104:107], v[216:219], v[108:111], 0
	v_mfma_f32_16x16x32_bf16 v[130:133], v[224:227], v[108:111], 0
	v_mfma_f32_16x16x32_bf16 v[104:107], v[220:223], v[60:63], v[104:107]
	v_mfma_f32_16x16x32_bf16 v[130:133], v[228:231], v[60:63], v[130:133]
	s_nop 7
	v_max3_f32 v154, v44, v45, s13
	v_max3_f32 v154, v46, v47, v154
	v_max3_f32 v154, v48, v49, v154
	v_max3_f32 v154, v50, v51, v154
	v_max3_f32 v154, v52, v53, v154
	v_max3_f32 v154, v54, v55, v154
	v_max3_f32 v154, v56, v57, v154
	v_max3_f32 v154, v58, v59, v154
	v_max3_f32 v154, v64, v65, v154
	v_max3_f32 v154, v66, v67, v154
	v_max3_f32 v154, v68, v69, v154
	v_max3_f32 v154, v70, v71, v154
	v_max3_f32 v154, v72, v73, v154
	v_max3_f32 v154, v74, v75, v154
	v_max3_f32 v154, v76, v77, v154
	v_max3_f32 v154, v78, v79, v154
	v_max3_f32 v154, v80, v81, v154
	v_max3_f32 v154, v82, v83, v154
	v_max3_f32 v154, v84, v85, v154
	v_max3_f32 v154, v86, v87, v154
	v_max3_f32 v154, v88, v89, v154
	v_max3_f32 v154, v90, v91, v154
	v_max3_f32 v154, v92, v93, v154
	v_max3_f32 v154, v94, v95, v154
	v_max3_f32 v154, v96, v97, v154
	v_max3_f32 v154, v98, v99, v154
	v_max3_f32 v154, v100, v101, v154
	v_max3_f32 v154, v102, v103, v154
	v_max3_f32 v154, v104, v105, v154
	v_max3_f32 v154, v106, v107, v154
	v_max3_f32 v154, v130, v131, v154
	v_max3_f32 v154, v132, v133, v154
	v_mov_b32_e32 v155, v154
	s_nop 1
	v_permlane16_swap_b32_e32 v154, v155
	v_max_f32_e32 v154, v154, v155
	v_mov_b32_e32 v155, v154
	s_nop 1
	v_permlane32_swap_b32_e32 v154, v155
	v_max_f32_e32 v154, v154, v155
	v_sub_f32_e32 v44, v44, v154
	v_exp_f32_e32 v44, v44
	v_sub_f32_e32 v45, v45, v154
	v_exp_f32_e32 v45, v45
	v_add_f32_e32 v172, 0, v44
	v_sub_f32_e32 v46, v46, v154
	v_exp_f32_e32 v46, v46
	v_add_f32_e32 v172, v45, v172
	v_sub_f32_e32 v47, v47, v154
	v_exp_f32_e32 v47, v47
	v_add_f32_e32 v172, v46, v172
	v_sub_f32_e32 v48, v48, v154
	v_exp_f32_e32 v48, v48
	v_add_f32_e32 v172, v47, v172
	v_sub_f32_e32 v49, v49, v154
	v_exp_f32_e32 v49, v49
	v_add_f32_e32 v172, v48, v172
	v_sub_f32_e32 v50, v50, v154
	v_exp_f32_e32 v50, v50
	v_add_f32_e32 v172, v49, v172
	v_sub_f32_e32 v51, v51, v154
	v_exp_f32_e32 v51, v51
	v_add_f32_e32 v172, v50, v172
	v_sub_f32_e32 v52, v52, v154
	v_exp_f32_e32 v52, v52
	v_add_f32_e32 v172, v51, v172
	v_sub_f32_e32 v53, v53, v154
	v_exp_f32_e32 v53, v53
	v_add_f32_e32 v172, v52, v172
	v_sub_f32_e32 v54, v54, v154
	v_exp_f32_e32 v54, v54
	v_add_f32_e32 v172, v53, v172
	v_sub_f32_e32 v55, v55, v154
	v_exp_f32_e32 v55, v55
	v_add_f32_e32 v172, v54, v172
	v_sub_f32_e32 v56, v56, v154
	v_exp_f32_e32 v56, v56
	v_add_f32_e32 v172, v55, v172
	v_sub_f32_e32 v57, v57, v154
	v_exp_f32_e32 v57, v57
	v_add_f32_e32 v172, v56, v172
	v_sub_f32_e32 v58, v58, v154
	v_exp_f32_e32 v58, v58
	v_add_f32_e32 v172, v57, v172
	v_sub_f32_e32 v59, v59, v154
	v_exp_f32_e32 v59, v59
	v_add_f32_e32 v172, v58, v172
	v_sub_f32_e32 v64, v64, v154
	v_exp_f32_e32 v64, v64
	v_add_f32_e32 v172, v59, v172
	v_sub_f32_e32 v65, v65, v154
	v_exp_f32_e32 v65, v65
	v_add_f32_e32 v172, v64, v172
	v_sub_f32_e32 v66, v66, v154
	v_exp_f32_e32 v66, v66
	v_add_f32_e32 v172, v65, v172
	v_sub_f32_e32 v67, v67, v154
	v_exp_f32_e32 v67, v67
	v_add_f32_e32 v172, v66, v172
	v_sub_f32_e32 v68, v68, v154
	v_exp_f32_e32 v68, v68
	v_add_f32_e32 v172, v67, v172
	v_sub_f32_e32 v69, v69, v154
	v_exp_f32_e32 v69, v69
	v_add_f32_e32 v172, v68, v172
	v_sub_f32_e32 v70, v70, v154
	v_exp_f32_e32 v70, v70
	v_add_f32_e32 v172, v69, v172
	v_sub_f32_e32 v71, v71, v154
	v_exp_f32_e32 v71, v71
	v_add_f32_e32 v172, v70, v172
	v_sub_f32_e32 v72, v72, v154
	v_exp_f32_e32 v72, v72
	v_add_f32_e32 v172, v71, v172
	v_sub_f32_e32 v73, v73, v154
	v_exp_f32_e32 v73, v73
	v_add_f32_e32 v172, v72, v172
	v_sub_f32_e32 v74, v74, v154
	v_exp_f32_e32 v74, v74
	v_add_f32_e32 v172, v73, v172
	v_sub_f32_e32 v75, v75, v154
	v_exp_f32_e32 v75, v75
	v_add_f32_e32 v172, v74, v172
	v_sub_f32_e32 v76, v76, v154
	v_exp_f32_e32 v76, v76
	v_add_f32_e32 v172, v75, v172
	v_sub_f32_e32 v77, v77, v154
	v_exp_f32_e32 v77, v77
	v_add_f32_e32 v172, v76, v172
	v_sub_f32_e32 v78, v78, v154
	v_exp_f32_e32 v78, v78
	v_add_f32_e32 v172, v77, v172
	v_sub_f32_e32 v79, v79, v154
	v_exp_f32_e32 v79, v79
	v_add_f32_e32 v172, v78, v172
	v_sub_f32_e32 v80, v80, v154
	v_exp_f32_e32 v80, v80
	v_add_f32_e32 v172, v79, v172
	v_sub_f32_e32 v81, v81, v154
	v_exp_f32_e32 v81, v81
	v_add_f32_e32 v172, v80, v172
	v_sub_f32_e32 v82, v82, v154
	v_exp_f32_e32 v82, v82
	v_add_f32_e32 v172, v81, v172
	v_sub_f32_e32 v83, v83, v154
	v_exp_f32_e32 v83, v83
	v_add_f32_e32 v172, v82, v172
	v_sub_f32_e32 v84, v84, v154
	v_exp_f32_e32 v84, v84
	v_add_f32_e32 v172, v83, v172
	v_sub_f32_e32 v85, v85, v154
	v_exp_f32_e32 v85, v85
	v_add_f32_e32 v172, v84, v172
	v_sub_f32_e32 v86, v86, v154
	v_exp_f32_e32 v86, v86
	v_add_f32_e32 v172, v85, v172
	v_sub_f32_e32 v87, v87, v154
	v_exp_f32_e32 v87, v87
	v_add_f32_e32 v172, v86, v172
	v_sub_f32_e32 v88, v88, v154
	v_exp_f32_e32 v88, v88
	v_add_f32_e32 v172, v87, v172
	v_sub_f32_e32 v89, v89, v154
	v_exp_f32_e32 v89, v89
	v_add_f32_e32 v172, v88, v172
	v_sub_f32_e32 v90, v90, v154
	v_exp_f32_e32 v90, v90
	v_add_f32_e32 v172, v89, v172
	v_sub_f32_e32 v91, v91, v154
	v_exp_f32_e32 v91, v91
	v_add_f32_e32 v172, v90, v172
	v_sub_f32_e32 v92, v92, v154
	v_exp_f32_e32 v92, v92
	v_add_f32_e32 v172, v91, v172
	v_sub_f32_e32 v93, v93, v154
	v_exp_f32_e32 v93, v93
	v_add_f32_e32 v172, v92, v172
	v_sub_f32_e32 v94, v94, v154
	v_exp_f32_e32 v94, v94
	v_add_f32_e32 v172, v93, v172
	v_sub_f32_e32 v95, v95, v154
	v_exp_f32_e32 v95, v95
	v_add_f32_e32 v172, v94, v172
	v_sub_f32_e32 v96, v96, v154
	v_exp_f32_e32 v96, v96
	v_add_f32_e32 v172, v95, v172
	v_sub_f32_e32 v97, v97, v154
	v_exp_f32_e32 v97, v97
	v_add_f32_e32 v172, v96, v172
	v_sub_f32_e32 v98, v98, v154
	v_exp_f32_e32 v98, v98
	v_add_f32_e32 v172, v97, v172
	v_sub_f32_e32 v99, v99, v154
	v_exp_f32_e32 v99, v99
	v_add_f32_e32 v172, v98, v172
	v_sub_f32_e32 v100, v100, v154
	v_exp_f32_e32 v100, v100
	v_add_f32_e32 v172, v99, v172
	v_sub_f32_e32 v101, v101, v154
	v_exp_f32_e32 v101, v101
	v_add_f32_e32 v172, v100, v172
	v_sub_f32_e32 v102, v102, v154
	v_exp_f32_e32 v102, v102
	v_add_f32_e32 v172, v101, v172
	v_sub_f32_e32 v103, v103, v154
	v_exp_f32_e32 v103, v103
	v_add_f32_e32 v172, v102, v172
	v_sub_f32_e32 v104, v104, v154
	v_exp_f32_e32 v104, v104
	v_add_f32_e32 v172, v103, v172
	v_sub_f32_e32 v105, v105, v154
	v_exp_f32_e32 v105, v105
	v_add_f32_e32 v172, v104, v172
	v_sub_f32_e32 v106, v106, v154
	v_exp_f32_e32 v106, v106
	v_add_f32_e32 v172, v105, v172
	v_sub_f32_e32 v107, v107, v154
	v_exp_f32_e32 v107, v107
	v_add_f32_e32 v172, v106, v172
	v_sub_f32_e32 v130, v130, v154
	v_exp_f32_e32 v130, v130
	v_add_f32_e32 v172, v107, v172
	v_sub_f32_e32 v131, v131, v154
	v_exp_f32_e32 v131, v131
	v_add_f32_e32 v172, v130, v172
	v_sub_f32_e32 v132, v132, v154
	v_exp_f32_e32 v132, v132
	v_add_f32_e32 v172, v131, v172
	v_sub_f32_e32 v133, v133, v154
	v_exp_f32_e32 v133, v133
	v_add_f32_e32 v172, v132, v172
	s_nop 0
	v_add_f32_e32 v172, v133, v172
	ds_read_b128 v[200:203], v150
	ds_read_b128 v[204:207], v151
	ds_read_b128 v[208:211], v152
	ds_read_b128 v[212:215], v153
	ds_read_b128 v[216:219], v150 offset:64
	ds_read_b128 v[220:223], v151 offset:64
	ds_read_b128 v[224:227], v152 offset:64
	ds_read_b128 v[228:231], v153 offset:64
	v_mov_b32_e32 v155, v172
	s_nop 1
	v_permlane16_swap_b32_e32 v172, v155
	v_add_f32_e32 v172, v172, v155
	v_mov_b32_e32 v155, v172
	s_nop 1
	v_permlane32_swap_b32_e32 v172, v155
	v_add_f32_e32 v172, v172, v155
	v_cvt_pk_bf16_f32 v44, v44, v45
	v_cvt_pk_bf16_f32 v45, v46, v47
	v_cvt_pk_bf16_f32 v46, v48, v49
	v_cvt_pk_bf16_f32 v47, v50, v51
	v_cvt_pk_bf16_f32 v52, v52, v53
	v_cvt_pk_bf16_f32 v53, v54, v55
	v_cvt_pk_bf16_f32 v54, v56, v57
	v_cvt_pk_bf16_f32 v55, v58, v59
	s_waitcnt lgkmcnt(4)
	s_nop 1
	v_mfma_f32_16x16x32_bf16 v[134:137], v[200:203], v[44:47], 0
	v_mfma_f32_16x16x32_bf16 v[138:141], v[204:207], v[44:47], 0
	v_mfma_f32_16x16x32_bf16 v[142:145], v[208:211], v[44:47], 0
	v_mfma_f32_16x16x32_bf16 v[146:149], v[212:215], v[44:47], 0
	ds_read_b128 v[200:203], v150 offset:128
	ds_read_b128 v[204:207], v151 offset:128
	ds_read_b128 v[208:211], v152 offset:128
	ds_read_b128 v[212:215], v153 offset:128
	v_cvt_pk_bf16_f32 v64, v64, v65
	v_cvt_pk_bf16_f32 v65, v66, v67
	v_cvt_pk_bf16_f32 v66, v68, v69
	v_cvt_pk_bf16_f32 v67, v70, v71
	s_waitcnt lgkmcnt(4)
	s_nop 1
	v_mfma_f32_16x16x32_bf16 v[134:137], v[216:219], v[52:55], v[134:137]
	v_mfma_f32_16x16x32_bf16 v[138:141], v[220:223], v[52:55], v[138:141]
	v_mfma_f32_16x16x32_bf16 v[142:145], v[224:227], v[52:55], v[142:145]
	v_mfma_f32_16x16x32_bf16 v[146:149], v[228:231], v[52:55], v[146:149]
	ds_read_b128 v[216:219], v150 offset:192
	ds_read_b128 v[220:223], v151 offset:192
	ds_read_b128 v[224:227], v152 offset:192
	ds_read_b128 v[228:231], v153 offset:192
	v_cvt_pk_bf16_f32 v72, v72, v73
	v_cvt_pk_bf16_f32 v73, v74, v75
	v_cvt_pk_bf16_f32 v74, v76, v77
	v_cvt_pk_bf16_f32 v75, v78, v79
	s_waitcnt lgkmcnt(4)
	s_nop 1
	v_mfma_f32_16x16x32_bf16 v[134:137], v[200:203], v[64:67], v[134:137]
	v_mfma_f32_16x16x32_bf16 v[138:141], v[204:207], v[64:67], v[138:141]
	v_mfma_f32_16x16x32_bf16 v[142:145], v[208:211], v[64:67], v[142:145]
	v_mfma_f32_16x16x32_bf16 v[146:149], v[212:215], v[64:67], v[146:149]
	ds_read_b128 v[200:203], v150 offset:256
	ds_read_b128 v[204:207], v151 offset:256
	ds_read_b128 v[208:211], v152 offset:256
	ds_read_b128 v[212:215], v153 offset:256
	v_cvt_pk_bf16_f32 v80, v80, v81
	v_cvt_pk_bf16_f32 v81, v82, v83
	v_cvt_pk_bf16_f32 v82, v84, v85
	v_cvt_pk_bf16_f32 v83, v86, v87
	s_waitcnt lgkmcnt(4)
	s_nop 1
	v_mfma_f32_16x16x32_bf16 v[134:137], v[216:219], v[72:75], v[134:137]
	v_mfma_f32_16x16x32_bf16 v[138:141], v[220:223], v[72:75], v[138:141]
	v_mfma_f32_16x16x32_bf16 v[142:145], v[224:227], v[72:75], v[142:145]
	v_mfma_f32_16x16x32_bf16 v[146:149], v[228:231], v[72:75], v[146:149]
	ds_read_b128 v[216:219], v150 offset:320
	ds_read_b128 v[220:223], v151 offset:320
	ds_read_b128 v[224:227], v152 offset:320
	ds_read_b128 v[228:231], v153 offset:320
	v_cvt_pk_bf16_f32 v88, v88, v89
	v_cvt_pk_bf16_f32 v89, v90, v91
	v_cvt_pk_bf16_f32 v90, v92, v93
	v_cvt_pk_bf16_f32 v91, v94, v95
	s_waitcnt lgkmcnt(4)
	s_nop 1
	v_mfma_f32_16x16x32_bf16 v[134:137], v[200:203], v[80:83], v[134:137]
	v_mfma_f32_16x16x32_bf16 v[138:141], v[204:207], v[80:83], v[138:141]
	v_mfma_f32_16x16x32_bf16 v[142:145], v[208:211], v[80:83], v[142:145]
	v_mfma_f32_16x16x32_bf16 v[146:149], v[212:215], v[80:83], v[146:149]
	ds_read_b128 v[200:203], v150 offset:384
	ds_read_b128 v[204:207], v151 offset:384
	ds_read_b128 v[208:211], v152 offset:384
	ds_read_b128 v[212:215], v153 offset:384
	v_cvt_pk_bf16_f32 v96, v96, v97
	v_cvt_pk_bf16_f32 v97, v98, v99
	v_cvt_pk_bf16_f32 v98, v100, v101
	v_cvt_pk_bf16_f32 v99, v102, v103
	s_waitcnt lgkmcnt(4)
	s_nop 1
	v_mfma_f32_16x16x32_bf16 v[134:137], v[216:219], v[88:91], v[134:137]
	v_mfma_f32_16x16x32_bf16 v[138:141], v[220:223], v[88:91], v[138:141]
	v_mfma_f32_16x16x32_bf16 v[142:145], v[224:227], v[88:91], v[142:145]
	v_mfma_f32_16x16x32_bf16 v[146:149], v[228:231], v[88:91], v[146:149]
	ds_read_b128 v[216:219], v150 offset:448
	ds_read_b128 v[220:223], v151 offset:448
	ds_read_b128 v[224:227], v152 offset:448
	ds_read_b128 v[228:231], v153 offset:448
	v_cvt_pk_bf16_f32 v104, v104, v105
	v_cvt_pk_bf16_f32 v105, v106, v107
	v_cvt_pk_bf16_f32 v106, v130, v131
	v_cvt_pk_bf16_f32 v107, v132, v133
	s_waitcnt lgkmcnt(4)
	s_nop 1
	v_mfma_f32_16x16x32_bf16 v[134:137], v[200:203], v[96:99], v[134:137]
	v_mfma_f32_16x16x32_bf16 v[138:141], v[204:207], v[96:99], v[138:141]
	v_mfma_f32_16x16x32_bf16 v[142:145], v[208:211], v[96:99], v[142:145]
	v_mfma_f32_16x16x32_bf16 v[146:149], v[212:215], v[96:99], v[146:149]
	s_waitcnt lgkmcnt(0)
	s_nop 1
	v_mfma_f32_16x16x32_bf16 v[134:137], v[216:219], v[104:107], v[134:137]
	v_mfma_f32_16x16x32_bf16 v[138:141], v[220:223], v[104:107], v[138:141]
	v_mfma_f32_16x16x32_bf16 v[142:145], v[224:227], v[104:107], v[142:145]
	v_mfma_f32_16x16x32_bf16 v[146:149], v[228:231], v[104:107], v[146:149]
	v_div_scale_f32 v173, s[8:9], v172, v172, 1.0
	v_rcp_f32_e32 v175, v173
	s_nop 0
	v_fma_f32 v176, -v173, v175, 1.0
	v_fmac_f32_e32 v175, v176, v175
	v_div_scale_f32 v174, vcc, 1.0, v172, 1.0
	v_mul_f32_e32 v177, v174, v175
	v_fma_f32 v176, -v173, v177, v174
	v_fmac_f32_e32 v177, v176, v175
	v_fma_f32 v173, -v173, v177, v174
	v_div_fmas_f32 v173, v173, v175, v177
	v_div_fixup_f32 v180, v173, v172, 1.0
	v_lshlrev_b64 v[182:183], 11, v[116:117]
	v_lshl_add_u64 v[182:183], s[0:1], 0, v[182:183]
	v_lshl_add_u64 v[182:183], v[182:183], 0, s[36:37]
	v_lshl_add_u64 v[182:183], v[182:183], 0, v[2:3]
	v_mul_f32_e32 v134, v180, v134
	v_mul_f32_e32 v135, v180, v135
	v_mul_f32_e32 v136, v180, v136
	v_mul_f32_e32 v137, v180, v137
	v_cvt_pk_bf16_f32 v184, v134, v135
	v_cvt_pk_bf16_f32 v185, v136, v137
	s_nop 0
	global_store_dwordx2 v[182:183], v[184:185], off offset:1536
	v_mul_f32_e32 v138, v180, v138
	v_mul_f32_e32 v139, v180, v139
	v_mul_f32_e32 v140, v180, v140
	v_mul_f32_e32 v141, v180, v141
	v_cvt_pk_bf16_f32 v186, v138, v139
	v_cvt_pk_bf16_f32 v187, v140, v141
	s_nop 0
	global_store_dwordx2 v[182:183], v[186:187], off offset:1568
	v_mul_f32_e32 v142, v180, v142
	v_mul_f32_e32 v143, v180, v143
	v_mul_f32_e32 v144, v180, v144
	v_mul_f32_e32 v145, v180, v145
	v_cvt_pk_bf16_f32 v188, v142, v143
	v_cvt_pk_bf16_f32 v189, v144, v145
	s_nop 0
	global_store_dwordx2 v[182:183], v[188:189], off offset:1600
	v_mul_f32_e32 v146, v180, v146
	v_mul_f32_e32 v147, v180, v147
	v_mul_f32_e32 v148, v180, v148
	v_mul_f32_e32 v149, v180, v149
	v_cvt_pk_bf16_f32 v190, v146, v147
	v_cvt_pk_bf16_f32 v191, v148, v149
	s_nop 0
	global_store_dwordx2 v[182:183], v[190:191], off offset:1632
	ds_read_b128 v[200:203], v128
	ds_read_b128 v[204:207], v128 offset:64
	ds_read_b128 v[208:211], v128 offset:2304
	ds_read_b128 v[212:215], v128 offset:2368
	ds_read_b128 v[216:219], v128 offset:4608
	ds_read_b128 v[220:223], v128 offset:4672
	ds_read_b128 v[224:227], v128 offset:6912
	ds_read_b128 v[228:231], v128 offset:6976
	s_waitcnt vmcnt(12)
	s_waitcnt lgkmcnt(4)
	v_mfma_f32_16x16x32_bf16 v[44:47], v[200:203], v[40:43], 0
	v_mfma_f32_16x16x32_bf16 v[48:51], v[208:211], v[40:43], 0
	v_mfma_f32_16x16x32_bf16 v[44:47], v[204:207], v[36:39], v[44:47]
	v_mfma_f32_16x16x32_bf16 v[48:51], v[212:215], v[36:39], v[48:51]
	ds_read_b128 v[200:203], v128 offset:9216
	ds_read_b128 v[204:207], v128 offset:9280
	ds_read_b128 v[208:211], v128 offset:11520
	ds_read_b128 v[212:215], v128 offset:11584
	s_waitcnt lgkmcnt(4)
	v_mfma_f32_16x16x32_bf16 v[52:55], v[216:219], v[40:43], 0
	v_mfma_f32_16x16x32_bf16 v[56:59], v[224:227], v[40:43], 0
	v_mfma_f32_16x16x32_bf16 v[52:55], v[220:223], v[36:39], v[52:55]
	v_mfma_f32_16x16x32_bf16 v[56:59], v[228:231], v[36:39], v[56:59]
	ds_read_b128 v[216:219], v128 offset:13824
	ds_read_b128 v[220:223], v128 offset:13888
	ds_read_b128 v[224:227], v128 offset:16128
	ds_read_b128 v[228:231], v128 offset:16192
	s_waitcnt lgkmcnt(4)
	v_mfma_f32_16x16x32_bf16 v[64:67], v[200:203], v[40:43], 0
	v_mfma_f32_16x16x32_bf16 v[68:71], v[208:211], v[40:43], 0
	v_mfma_f32_16x16x32_bf16 v[64:67], v[204:207], v[36:39], v[64:67]
	v_mfma_f32_16x16x32_bf16 v[68:71], v[212:215], v[36:39], v[68:71]
	ds_read_b128 v[200:203], v128 offset:18432
	ds_read_b128 v[204:207], v128 offset:18496
	ds_read_b128 v[208:211], v128 offset:20736
	ds_read_b128 v[212:215], v128 offset:20800
	s_waitcnt lgkmcnt(4)
	v_mfma_f32_16x16x32_bf16 v[72:75], v[216:219], v[40:43], 0
	v_mfma_f32_16x16x32_bf16 v[76:79], v[224:227], v[40:43], 0
	v_mfma_f32_16x16x32_bf16 v[72:75], v[220:223], v[36:39], v[72:75]
	v_mfma_f32_16x16x32_bf16 v[76:79], v[228:231], v[36:39], v[76:79]
	ds_read_b128 v[216:219], v128 offset:23040
	ds_read_b128 v[220:223], v128 offset:23104
	ds_read_b128 v[224:227], v128 offset:25344
	ds_read_b128 v[228:231], v128 offset:25408
	s_waitcnt lgkmcnt(4)
	v_mfma_f32_16x16x32_bf16 v[80:83], v[200:203], v[40:43], 0
	v_mfma_f32_16x16x32_bf16 v[84:87], v[208:211], v[40:43], 0
	v_mfma_f32_16x16x32_bf16 v[80:83], v[204:207], v[36:39], v[80:83]
	v_mfma_f32_16x16x32_bf16 v[84:87], v[212:215], v[36:39], v[84:87]
	ds_read_b128 v[200:203], v128 offset:27648
	ds_read_b128 v[204:207], v128 offset:27712
	ds_read_b128 v[208:211], v128 offset:29952
	ds_read_b128 v[212:215], v128 offset:30016
	s_waitcnt lgkmcnt(4)
	v_mfma_f32_16x16x32_bf16 v[88:91], v[216:219], v[40:43], 0
	v_mfma_f32_16x16x32_bf16 v[92:95], v[224:227], v[40:43], 0
	v_mfma_f32_16x16x32_bf16 v[88:91], v[220:223], v[36:39], v[88:91]
	v_mfma_f32_16x16x32_bf16 v[92:95], v[228:231], v[36:39], v[92:95]
	ds_read_b128 v[216:219], v128 offset:32256
	ds_read_b128 v[220:223], v128 offset:32320
	ds_read_b128 v[224:227], v128 offset:34560
	ds_read_b128 v[228:231], v128 offset:34624
	s_waitcnt lgkmcnt(4)
	v_mfma_f32_16x16x32_bf16 v[96:99], v[200:203], v[40:43], 0
	v_mfma_f32_16x16x32_bf16 v[100:103], v[208:211], v[40:43], 0
	v_mfma_f32_16x16x32_bf16 v[96:99], v[204:207], v[36:39], v[96:99]
	v_mfma_f32_16x16x32_bf16 v[100:103], v[212:215], v[36:39], v[100:103]
	s_waitcnt lgkmcnt(0)
	v_mfma_f32_16x16x32_bf16 v[104:107], v[216:219], v[40:43], 0
	v_mfma_f32_16x16x32_bf16 v[130:133], v[224:227], v[40:43], 0
	v_mfma_f32_16x16x32_bf16 v[104:107], v[220:223], v[36:39], v[104:107]
	v_mfma_f32_16x16x32_bf16 v[130:133], v[228:231], v[36:39], v[130:133]
	s_nop 7
	v_max3_f32 v154, v44, v45, s13
	v_max3_f32 v154, v46, v47, v154
	v_max3_f32 v154, v48, v49, v154
	v_max3_f32 v154, v50, v51, v154
	v_max3_f32 v154, v52, v53, v154
	v_max3_f32 v154, v54, v55, v154
	v_max3_f32 v154, v56, v57, v154
	v_max3_f32 v154, v58, v59, v154
	v_max3_f32 v154, v64, v65, v154
	v_max3_f32 v154, v66, v67, v154
	v_max3_f32 v154, v68, v69, v154
	v_max3_f32 v154, v70, v71, v154
	v_max3_f32 v154, v72, v73, v154
	v_max3_f32 v154, v74, v75, v154
	v_max3_f32 v154, v76, v77, v154
	v_max3_f32 v154, v78, v79, v154
	v_max3_f32 v154, v80, v81, v154
	v_max3_f32 v154, v82, v83, v154
	v_max3_f32 v154, v84, v85, v154
	v_max3_f32 v154, v86, v87, v154
	v_max3_f32 v154, v88, v89, v154
	v_max3_f32 v154, v90, v91, v154
	v_max3_f32 v154, v92, v93, v154
	v_max3_f32 v154, v94, v95, v154
	v_max3_f32 v154, v96, v97, v154
	v_max3_f32 v154, v98, v99, v154
	v_max3_f32 v154, v100, v101, v154
	v_max3_f32 v154, v102, v103, v154
	v_max3_f32 v154, v104, v105, v154
	v_max3_f32 v154, v106, v107, v154
	v_max3_f32 v154, v130, v131, v154
	v_max3_f32 v154, v132, v133, v154
	v_mov_b32_e32 v155, v154
	s_nop 1
	v_permlane16_swap_b32_e32 v154, v155
	v_max_f32_e32 v154, v154, v155
	v_mov_b32_e32 v155, v154
	s_nop 1
	v_permlane32_swap_b32_e32 v154, v155
	v_max_f32_e32 v154, v154, v155
	v_sub_f32_e32 v44, v44, v154
	v_exp_f32_e32 v44, v44
	v_sub_f32_e32 v45, v45, v154
	v_exp_f32_e32 v45, v45
	v_add_f32_e32 v172, 0, v44
	v_sub_f32_e32 v46, v46, v154
	v_exp_f32_e32 v46, v46
	v_add_f32_e32 v172, v45, v172
	v_sub_f32_e32 v47, v47, v154
	v_exp_f32_e32 v47, v47
	v_add_f32_e32 v172, v46, v172
	v_sub_f32_e32 v48, v48, v154
	v_exp_f32_e32 v48, v48
	v_add_f32_e32 v172, v47, v172
	v_sub_f32_e32 v49, v49, v154
	v_exp_f32_e32 v49, v49
	v_add_f32_e32 v172, v48, v172
	v_sub_f32_e32 v50, v50, v154
	v_exp_f32_e32 v50, v50
	v_add_f32_e32 v172, v49, v172
	v_sub_f32_e32 v51, v51, v154
	v_exp_f32_e32 v51, v51
	v_add_f32_e32 v172, v50, v172
	v_sub_f32_e32 v52, v52, v154
	v_exp_f32_e32 v52, v52
	v_add_f32_e32 v172, v51, v172
	v_sub_f32_e32 v53, v53, v154
	v_exp_f32_e32 v53, v53
	v_add_f32_e32 v172, v52, v172
	v_sub_f32_e32 v54, v54, v154
	v_exp_f32_e32 v54, v54
	v_add_f32_e32 v172, v53, v172
	v_sub_f32_e32 v55, v55, v154
	v_exp_f32_e32 v55, v55
	v_add_f32_e32 v172, v54, v172
	v_sub_f32_e32 v56, v56, v154
	v_exp_f32_e32 v56, v56
	v_add_f32_e32 v172, v55, v172
	v_sub_f32_e32 v57, v57, v154
	v_exp_f32_e32 v57, v57
	v_add_f32_e32 v172, v56, v172
	v_sub_f32_e32 v58, v58, v154
	v_exp_f32_e32 v58, v58
	v_add_f32_e32 v172, v57, v172
	v_sub_f32_e32 v59, v59, v154
	v_exp_f32_e32 v59, v59
	v_add_f32_e32 v172, v58, v172
	v_sub_f32_e32 v64, v64, v154
	v_exp_f32_e32 v64, v64
	v_add_f32_e32 v172, v59, v172
	v_sub_f32_e32 v65, v65, v154
	v_exp_f32_e32 v65, v65
	v_add_f32_e32 v172, v64, v172
	v_sub_f32_e32 v66, v66, v154
	v_exp_f32_e32 v66, v66
	v_add_f32_e32 v172, v65, v172
	v_sub_f32_e32 v67, v67, v154
	v_exp_f32_e32 v67, v67
	v_add_f32_e32 v172, v66, v172
	v_sub_f32_e32 v68, v68, v154
	v_exp_f32_e32 v68, v68
	v_add_f32_e32 v172, v67, v172
	v_sub_f32_e32 v69, v69, v154
	v_exp_f32_e32 v69, v69
	v_add_f32_e32 v172, v68, v172
	v_sub_f32_e32 v70, v70, v154
	v_exp_f32_e32 v70, v70
	v_add_f32_e32 v172, v69, v172
	v_sub_f32_e32 v71, v71, v154
	v_exp_f32_e32 v71, v71
	v_add_f32_e32 v172, v70, v172
	v_sub_f32_e32 v72, v72, v154
	v_exp_f32_e32 v72, v72
	v_add_f32_e32 v172, v71, v172
	v_sub_f32_e32 v73, v73, v154
	v_exp_f32_e32 v73, v73
	v_add_f32_e32 v172, v72, v172
	v_sub_f32_e32 v74, v74, v154
	v_exp_f32_e32 v74, v74
	v_add_f32_e32 v172, v73, v172
	v_sub_f32_e32 v75, v75, v154
	v_exp_f32_e32 v75, v75
	v_add_f32_e32 v172, v74, v172
	v_sub_f32_e32 v76, v76, v154
	v_exp_f32_e32 v76, v76
	v_add_f32_e32 v172, v75, v172
	v_sub_f32_e32 v77, v77, v154
	v_exp_f32_e32 v77, v77
	v_add_f32_e32 v172, v76, v172
	v_sub_f32_e32 v78, v78, v154
	v_exp_f32_e32 v78, v78
	v_add_f32_e32 v172, v77, v172
	v_sub_f32_e32 v79, v79, v154
	v_exp_f32_e32 v79, v79
	v_add_f32_e32 v172, v78, v172
	v_sub_f32_e32 v80, v80, v154
	v_exp_f32_e32 v80, v80
	v_add_f32_e32 v172, v79, v172
	v_sub_f32_e32 v81, v81, v154
	v_exp_f32_e32 v81, v81
	v_add_f32_e32 v172, v80, v172
	v_sub_f32_e32 v82, v82, v154
	v_exp_f32_e32 v82, v82
	v_add_f32_e32 v172, v81, v172
	v_sub_f32_e32 v83, v83, v154
	v_exp_f32_e32 v83, v83
	v_add_f32_e32 v172, v82, v172
	v_sub_f32_e32 v84, v84, v154
	v_exp_f32_e32 v84, v84
	v_add_f32_e32 v172, v83, v172
	v_sub_f32_e32 v85, v85, v154
	v_exp_f32_e32 v85, v85
	v_add_f32_e32 v172, v84, v172
	v_sub_f32_e32 v86, v86, v154
	v_exp_f32_e32 v86, v86
	v_add_f32_e32 v172, v85, v172
	v_sub_f32_e32 v87, v87, v154
	v_exp_f32_e32 v87, v87
	v_add_f32_e32 v172, v86, v172
	v_sub_f32_e32 v88, v88, v154
	v_exp_f32_e32 v88, v88
	v_add_f32_e32 v172, v87, v172
	v_sub_f32_e32 v89, v89, v154
	v_exp_f32_e32 v89, v89
	v_add_f32_e32 v172, v88, v172
	v_sub_f32_e32 v90, v90, v154
	v_exp_f32_e32 v90, v90
	v_add_f32_e32 v172, v89, v172
	v_sub_f32_e32 v91, v91, v154
	v_exp_f32_e32 v91, v91
	v_add_f32_e32 v172, v90, v172
	v_sub_f32_e32 v92, v92, v154
	v_exp_f32_e32 v92, v92
	v_add_f32_e32 v172, v91, v172
	v_sub_f32_e32 v93, v93, v154
	v_exp_f32_e32 v93, v93
	v_add_f32_e32 v172, v92, v172
	v_sub_f32_e32 v94, v94, v154
	v_exp_f32_e32 v94, v94
	v_add_f32_e32 v172, v93, v172
	v_sub_f32_e32 v95, v95, v154
	v_exp_f32_e32 v95, v95
	v_add_f32_e32 v172, v94, v172
	v_sub_f32_e32 v96, v96, v154
	v_exp_f32_e32 v96, v96
	v_add_f32_e32 v172, v95, v172
	v_sub_f32_e32 v97, v97, v154
	v_exp_f32_e32 v97, v97
	v_add_f32_e32 v172, v96, v172
	v_sub_f32_e32 v98, v98, v154
	v_exp_f32_e32 v98, v98
	v_add_f32_e32 v172, v97, v172
	v_sub_f32_e32 v99, v99, v154
	v_exp_f32_e32 v99, v99
	v_add_f32_e32 v172, v98, v172
	v_sub_f32_e32 v100, v100, v154
	v_exp_f32_e32 v100, v100
	v_add_f32_e32 v172, v99, v172
	v_sub_f32_e32 v101, v101, v154
	v_exp_f32_e32 v101, v101
	v_add_f32_e32 v172, v100, v172
	v_sub_f32_e32 v102, v102, v154
	v_exp_f32_e32 v102, v102
	v_add_f32_e32 v172, v101, v172
	v_sub_f32_e32 v103, v103, v154
	v_exp_f32_e32 v103, v103
	v_add_f32_e32 v172, v102, v172
	v_sub_f32_e32 v104, v104, v154
	v_exp_f32_e32 v104, v104
	v_add_f32_e32 v172, v103, v172
	v_sub_f32_e32 v105, v105, v154
	v_exp_f32_e32 v105, v105
	v_add_f32_e32 v172, v104, v172
	v_sub_f32_e32 v106, v106, v154
	v_exp_f32_e32 v106, v106
	v_add_f32_e32 v172, v105, v172
	v_sub_f32_e32 v107, v107, v154
	v_exp_f32_e32 v107, v107
	v_add_f32_e32 v172, v106, v172
	v_sub_f32_e32 v130, v130, v154
	v_exp_f32_e32 v130, v130
	v_add_f32_e32 v172, v107, v172
	v_sub_f32_e32 v131, v131, v154
	v_exp_f32_e32 v131, v131
	v_add_f32_e32 v172, v130, v172
	v_sub_f32_e32 v132, v132, v154
	v_exp_f32_e32 v132, v132
	v_add_f32_e32 v172, v131, v172
	v_sub_f32_e32 v133, v133, v154
	v_exp_f32_e32 v133, v133
	v_add_f32_e32 v172, v132, v172
	s_nop 0
	v_add_f32_e32 v172, v133, v172
	ds_read_b128 v[200:203], v150
	ds_read_b128 v[204:207], v151
	ds_read_b128 v[208:211], v152
	ds_read_b128 v[212:215], v153
	ds_read_b128 v[216:219], v150 offset:64
	ds_read_b128 v[220:223], v151 offset:64
	ds_read_b128 v[224:227], v152 offset:64
	ds_read_b128 v[228:231], v153 offset:64
	v_mov_b32_e32 v155, v172
	s_nop 1
	v_permlane16_swap_b32_e32 v172, v155
	v_add_f32_e32 v172, v172, v155
	v_mov_b32_e32 v155, v172
	s_nop 1
	v_permlane32_swap_b32_e32 v172, v155
	v_add_f32_e32 v172, v172, v155
	v_cvt_pk_bf16_f32 v44, v44, v45
	v_cvt_pk_bf16_f32 v45, v46, v47
	v_cvt_pk_bf16_f32 v46, v48, v49
	v_cvt_pk_bf16_f32 v47, v50, v51
	v_cvt_pk_bf16_f32 v52, v52, v53
	v_cvt_pk_bf16_f32 v53, v54, v55
	v_cvt_pk_bf16_f32 v54, v56, v57
	v_cvt_pk_bf16_f32 v55, v58, v59
	s_waitcnt lgkmcnt(4)
	s_nop 1
	v_mfma_f32_16x16x32_bf16 v[134:137], v[200:203], v[44:47], 0
	v_mfma_f32_16x16x32_bf16 v[138:141], v[204:207], v[44:47], 0
	v_mfma_f32_16x16x32_bf16 v[142:145], v[208:211], v[44:47], 0
	v_mfma_f32_16x16x32_bf16 v[146:149], v[212:215], v[44:47], 0
	ds_read_b128 v[200:203], v150 offset:128
	ds_read_b128 v[204:207], v151 offset:128
	ds_read_b128 v[208:211], v152 offset:128
	ds_read_b128 v[212:215], v153 offset:128
	v_cvt_pk_bf16_f32 v64, v64, v65
	v_cvt_pk_bf16_f32 v65, v66, v67
	v_cvt_pk_bf16_f32 v66, v68, v69
	v_cvt_pk_bf16_f32 v67, v70, v71
	s_waitcnt lgkmcnt(4)
	s_nop 1
	v_mfma_f32_16x16x32_bf16 v[134:137], v[216:219], v[52:55], v[134:137]
	v_mfma_f32_16x16x32_bf16 v[138:141], v[220:223], v[52:55], v[138:141]
	v_mfma_f32_16x16x32_bf16 v[142:145], v[224:227], v[52:55], v[142:145]
	v_mfma_f32_16x16x32_bf16 v[146:149], v[228:231], v[52:55], v[146:149]
	ds_read_b128 v[216:219], v150 offset:192
	ds_read_b128 v[220:223], v151 offset:192
	ds_read_b128 v[224:227], v152 offset:192
	ds_read_b128 v[228:231], v153 offset:192
	v_cvt_pk_bf16_f32 v72, v72, v73
	v_cvt_pk_bf16_f32 v73, v74, v75
	v_cvt_pk_bf16_f32 v74, v76, v77
	v_cvt_pk_bf16_f32 v75, v78, v79
	s_waitcnt lgkmcnt(4)
	s_nop 1
	v_mfma_f32_16x16x32_bf16 v[134:137], v[200:203], v[64:67], v[134:137]
	v_mfma_f32_16x16x32_bf16 v[138:141], v[204:207], v[64:67], v[138:141]
	v_mfma_f32_16x16x32_bf16 v[142:145], v[208:211], v[64:67], v[142:145]
	v_mfma_f32_16x16x32_bf16 v[146:149], v[212:215], v[64:67], v[146:149]
	ds_read_b128 v[200:203], v150 offset:256
	ds_read_b128 v[204:207], v151 offset:256
	ds_read_b128 v[208:211], v152 offset:256
	ds_read_b128 v[212:215], v153 offset:256
	v_cvt_pk_bf16_f32 v80, v80, v81
	v_cvt_pk_bf16_f32 v81, v82, v83
	v_cvt_pk_bf16_f32 v82, v84, v85
	v_cvt_pk_bf16_f32 v83, v86, v87
	s_waitcnt lgkmcnt(4)
	s_nop 1
	v_mfma_f32_16x16x32_bf16 v[134:137], v[216:219], v[72:75], v[134:137]
	v_mfma_f32_16x16x32_bf16 v[138:141], v[220:223], v[72:75], v[138:141]
	v_mfma_f32_16x16x32_bf16 v[142:145], v[224:227], v[72:75], v[142:145]
	v_mfma_f32_16x16x32_bf16 v[146:149], v[228:231], v[72:75], v[146:149]
	ds_read_b128 v[216:219], v150 offset:320
	ds_read_b128 v[220:223], v151 offset:320
	ds_read_b128 v[224:227], v152 offset:320
	ds_read_b128 v[228:231], v153 offset:320
	v_cvt_pk_bf16_f32 v88, v88, v89
	v_cvt_pk_bf16_f32 v89, v90, v91
	v_cvt_pk_bf16_f32 v90, v92, v93
	v_cvt_pk_bf16_f32 v91, v94, v95
	s_waitcnt lgkmcnt(4)
	s_nop 1
	v_mfma_f32_16x16x32_bf16 v[134:137], v[200:203], v[80:83], v[134:137]
	v_mfma_f32_16x16x32_bf16 v[138:141], v[204:207], v[80:83], v[138:141]
	v_mfma_f32_16x16x32_bf16 v[142:145], v[208:211], v[80:83], v[142:145]
	v_mfma_f32_16x16x32_bf16 v[146:149], v[212:215], v[80:83], v[146:149]
	ds_read_b128 v[200:203], v150 offset:384
	ds_read_b128 v[204:207], v151 offset:384
	ds_read_b128 v[208:211], v152 offset:384
	ds_read_b128 v[212:215], v153 offset:384
	v_cvt_pk_bf16_f32 v96, v96, v97
	v_cvt_pk_bf16_f32 v97, v98, v99
	v_cvt_pk_bf16_f32 v98, v100, v101
	v_cvt_pk_bf16_f32 v99, v102, v103
	s_waitcnt lgkmcnt(4)
	s_nop 1
	v_mfma_f32_16x16x32_bf16 v[134:137], v[216:219], v[88:91], v[134:137]
	v_mfma_f32_16x16x32_bf16 v[138:141], v[220:223], v[88:91], v[138:141]
	v_mfma_f32_16x16x32_bf16 v[142:145], v[224:227], v[88:91], v[142:145]
	v_mfma_f32_16x16x32_bf16 v[146:149], v[228:231], v[88:91], v[146:149]
	ds_read_b128 v[216:219], v150 offset:448
	ds_read_b128 v[220:223], v151 offset:448
	ds_read_b128 v[224:227], v152 offset:448
	ds_read_b128 v[228:231], v153 offset:448
	v_cvt_pk_bf16_f32 v104, v104, v105
	v_cvt_pk_bf16_f32 v105, v106, v107
	v_cvt_pk_bf16_f32 v106, v130, v131
	v_cvt_pk_bf16_f32 v107, v132, v133
	s_waitcnt lgkmcnt(4)
	s_nop 1
	v_mfma_f32_16x16x32_bf16 v[134:137], v[200:203], v[96:99], v[134:137]
	v_mfma_f32_16x16x32_bf16 v[138:141], v[204:207], v[96:99], v[138:141]
	v_mfma_f32_16x16x32_bf16 v[142:145], v[208:211], v[96:99], v[142:145]
	v_mfma_f32_16x16x32_bf16 v[146:149], v[212:215], v[96:99], v[146:149]
	s_waitcnt lgkmcnt(0)
	s_nop 1
	v_mfma_f32_16x16x32_bf16 v[134:137], v[216:219], v[104:107], v[134:137]
	v_mfma_f32_16x16x32_bf16 v[138:141], v[220:223], v[104:107], v[138:141]
	v_mfma_f32_16x16x32_bf16 v[142:145], v[224:227], v[104:107], v[142:145]
	v_mfma_f32_16x16x32_bf16 v[146:149], v[228:231], v[104:107], v[146:149]
	v_div_scale_f32 v173, s[8:9], v172, v172, 1.0
	v_rcp_f32_e32 v175, v173
	s_nop 0
	v_fma_f32 v176, -v173, v175, 1.0
	v_fmac_f32_e32 v175, v176, v175
	v_div_scale_f32 v174, vcc, 1.0, v172, 1.0
	v_mul_f32_e32 v177, v174, v175
	v_fma_f32 v176, -v173, v177, v174
	v_fmac_f32_e32 v177, v176, v175
	v_fma_f32 v173, -v173, v177, v174
	v_div_fmas_f32 v173, v173, v175, v177
	v_div_fixup_f32 v180, v173, v172, 1.0
	v_lshlrev_b64 v[182:183], 11, v[114:115]
	v_lshl_add_u64 v[182:183], s[0:1], 0, v[182:183]
	v_lshl_add_u64 v[182:183], v[182:183], 0, s[36:37]
	v_lshl_add_u64 v[182:183], v[182:183], 0, v[2:3]
	v_mul_f32_e32 v134, v180, v134
	v_mul_f32_e32 v135, v180, v135
	v_mul_f32_e32 v136, v180, v136
	v_mul_f32_e32 v137, v180, v137
	v_cvt_pk_bf16_f32 v184, v134, v135
	v_cvt_pk_bf16_f32 v185, v136, v137
	s_nop 0
	global_store_dwordx2 v[182:183], v[184:185], off offset:1536
	v_mul_f32_e32 v138, v180, v138
	v_mul_f32_e32 v139, v180, v139
	v_mul_f32_e32 v140, v180, v140
	v_mul_f32_e32 v141, v180, v141
	v_cvt_pk_bf16_f32 v186, v138, v139
	v_cvt_pk_bf16_f32 v187, v140, v141
	s_nop 0
	global_store_dwordx2 v[182:183], v[186:187], off offset:1568
	v_mul_f32_e32 v142, v180, v142
	v_mul_f32_e32 v143, v180, v143
	v_mul_f32_e32 v144, v180, v144
	v_mul_f32_e32 v145, v180, v145
	v_cvt_pk_bf16_f32 v188, v142, v143
	v_cvt_pk_bf16_f32 v189, v144, v145
	s_nop 0
	global_store_dwordx2 v[182:183], v[188:189], off offset:1600
	v_mul_f32_e32 v146, v180, v146
	v_mul_f32_e32 v147, v180, v147
	v_mul_f32_e32 v148, v180, v148
	v_mul_f32_e32 v149, v180, v149
	v_cvt_pk_bf16_f32 v190, v146, v147
	v_cvt_pk_bf16_f32 v191, v148, v149
	s_nop 0
	global_store_dwordx2 v[182:183], v[190:191], off offset:1632
	s_mov_b32 s13, s12
	s_andn2_b64 vcc, exec, s[6:7]
	s_barrier
	s_cbranch_vccz .LBB0_582
